# P5a->P5b: cross-attention units remapped to the CU that produced their query tile; XCD barrier replaced by workgroup barrier (G=256 only)
# speedup vs baseline: 1.0146x; 1.0021x over previous
; __device__ __forceinline__ int hw_lane() { int l = (int)__builtin_amdgcn_mbcnt_hi(~0u, __builtin_amdgcn_mbcnt_lo(~0u, 0u)); asm volatile("" : "+v"(l)); return l; }
; #define XCD_BAR() do { if (use_xcd) { xbar_target += (unsigned)(G / 8); xcd_local_bar((unsigned*)opq_ptr(args.ws) + 64 * (1 + (blk & 7)), xbar_target, wave == 0 && hw_lane() == 0); } else GRID_BAR(); } while (0)
; __global__ void __launch_bounds__(NTHR, 2) hybrid_fwd(Args args) {
;     ...
;     XCD_BAR();
;     ...
;     { const int lane = hw_lane(); const int upb = ((T / 256) * 4 + G - 1) / G; for (int i = 0; i < upb; ++i) { const int un = hb * upb + i; if (un >= (T / 256) * 4) break; xattn_unit(un >> 2, un & 3, QX, KX, VXT, OX, wave, lane, ldsl); } }
.LBB0_621:
	s_cmp_eq_u32 s20, 0x100
	s_cbranch_scc0 .Lp5a_bar_orig
	s_waitcnt vmcnt(0) lgkmcnt(0)
	s_barrier
	s_branch .LBB0_642

; __device__ __forceinline__ int hw_lane() { int l = (int)__builtin_amdgcn_mbcnt_hi(~0u, __builtin_amdgcn_mbcnt_lo(~0u, 0u)); asm volatile("" : "+v"(l)); return l; }
; #define LAS __attribute__((address_space(3)))
; __device__ __forceinline__ void xattn_unit(int tb, int h, const bf16* QX, const bf16* KX, const bf16* VXT, bf16* OX, int wid, int lane, LAS unsigned char* ldsl) {
;     const int r32 = lane & 31, hi = lane >> 5, b = tb >> 3, tid = wid * 64 + lane;
;     const size_t qrow = (size_t)tb * 256 + wid * 32 + r32;
;     bf16x8 qr[8];
; #pragma unroll
;     for (int d0 = 0; d0 < 8; ++d0) qr[d0] = *(const bf16x8*)(QX + qrow * 512 + h * 128 + d0 * 16 + hi * 8);
;     {
;         u32x4 kt[8], vt[8];
; #pragma unroll
;         for (int i = 0; i < 8; ++i) { const int idx = tid + i * NTHR, key = idx >> 4, c = idx & 15; kt[i] = *(const u32x4*)(KX + ((size_t)b * 256 + key) * 512 + h * 128 + c * 8); }
; #pragma unroll
;         for (int i = 0; i < 8; ++i) { const int idx = tid + i * NTHR, d = idx >> 5, q = idx & 31; vt[i] = *(const u32x4*)(VXT + ((size_t)(b * 4 + h) * 128 + d) * 256 + q * 8); }
; #pragma unroll
;         for (int i = 0; i < 8; ++i) { const int idx = tid + i * NTHR, key = idx >> 4, c = idx & 15; *(LAS u32x4*)(ldsl + ((((key >> 5) * 16 + c) * 32 + (key & 31)) * 16)) = kt[i]; }
; #pragma unroll
;         for (int i = 0; i < 8; ++i) { const int idx = tid + i * NTHR, d = idx >> 5, q = idx & 31; *(LAS u32x4*)(ldsl + 65536 + (((((q >> 2) * 4 + (d >> 5)) * 4 + (q & 3)) * 32 + (d & 31)) * 16)) = vt[i]; }
; __global__ void __launch_bounds__(NTHR, 2) hybrid_fwd(Args args) {
;     ...
;     { const int lane = hw_lane(); const int upb = ((T / 256) * 4 + G - 1) / G; for (int i = 0; i < upb; ++i) { const int un = hb * upb + i; if (un >= (T / 256) * 4) break; xattn_unit(un >> 2, un & 3, QX, KX, VXT, OX, wave, lane, ldsl); } }
.LBB0_654:
	s_add_i32 s12, s20, 0x1ff
	s_ashr_i32 s13, s12, 31
	s_abs_i32 s12, s12
	s_mul_hi_u32 s14, s12, s62
	s_mul_i32 s15, s14, s61
	s_sub_i32 s12, s12, s15
	s_xor_b32 s13, s13, s21
	s_add_i32 s15, s14, 1
	s_sub_i32 s25, s12, s61
	s_cmp_ge_u32 s12, s61
	s_cselect_b32 s14, s15, s14
	s_cselect_b32 s12, s25, s12
	s_add_i32 s15, s14, 1
	s_cmp_ge_u32 s12, s61
	s_cselect_b32 s12, s15, s14
	s_xor_b32 s12, s12, s13
	s_sub_i32 s30, s12, s13
	v_mov_b32_e32 v0, v212
	s_cmp_lt_i32 s30, 1
	s_cbranch_scc1 .LBB0_661
	v_add_u32_e32 v3, s71, v0
	v_ashrrev_i32_e32 v4, 4, v3
	v_ashrrev_i32_e32 v5, 31, v4
	v_add_u32_e32 v6, 0x200, v3
	v_lshlrev_b64 v[124:125], 10, v[4:5]
	v_ashrrev_i32_e32 v4, 4, v6
	v_ashrrev_i32_e32 v5, 31, v4
	v_add_u32_e32 v7, 0x400, v3
	v_lshlrev_b64 v[126:127], 10, v[4:5]
	v_ashrrev_i32_e32 v4, 4, v7
	v_ashrrev_i32_e32 v5, 31, v4
	v_add_u32_e32 v8, 0x600, v3
	v_lshlrev_b64 v[128:129], 10, v[4:5]
	v_ashrrev_i32_e32 v4, 4, v8
	v_ashrrev_i32_e32 v5, 31, v4
	v_add_u32_e32 v9, 0x800, v3
	v_lshlrev_b64 v[130:131], 10, v[4:5]
	v_ashrrev_i32_e32 v4, 4, v9
	v_ashrrev_i32_e32 v5, 31, v4
	v_add_u32_e32 v10, 0xa00, v3
	v_lshlrev_b64 v[132:133], 10, v[4:5]
	v_ashrrev_i32_e32 v4, 4, v10
	v_ashrrev_i32_e32 v5, 31, v4
	v_add_u32_e32 v11, 0xc00, v3
	v_lshlrev_b64 v[134:135], 10, v[4:5]
	v_ashrrev_i32_e32 v4, 4, v11
	v_ashrrev_i32_e32 v5, 31, v4
	v_add_u32_e32 v12, 0xe00, v3
	v_lshlrev_b64 v[136:137], 10, v[4:5]
	v_ashrrev_i32_e32 v4, 4, v12
	v_mov_b32_e32 v121, 0
	v_ashrrev_i32_e32 v5, 31, v4
	v_lshlrev_b32_e32 v13, 4, v0
	v_lshlrev_b64 v[138:139], 10, v[4:5]
	v_and_b32_e32 v4, 0x1f0, v13
	v_mov_b32_e32 v5, v121
	s_mul_i32 s31, s30, s24
	s_cmp_eq_u32 s20, 0x100
	s_cbranch_scc0 .Lp5b_keepmap
	s_lshr_b32 s98, s24, 4
	s_lshl_b32 s98, s98, 3
	s_and_b32 s99, s24, 7
	s_add_i32 s98, s98, s99
	s_lshl_b32 s98, s98, 2
	s_bfe_u32 s99, s24, 0x10003
	s_lshl_b32 s99, s99, 1
	s_add_i32 s31, s98, s99
.Lp5b_keepmap:
	v_lshl_add_u64 v[4:5], s[26:27], 0, v[4:5]
	s_mov_b64 s[24:25], 0x2e00000
	v_lshl_add_u64 v[140:141], v[4:5], 0, s[24:25]
	v_ashrrev_i32_e32 v4, 5, v3
	v_ashrrev_i32_e32 v5, 31, v4
	v_lshlrev_b64 v[142:143], 9, v[4:5]
	v_ashrrev_i32_e32 v4, 5, v6
	v_ashrrev_i32_e32 v5, 31, v4
	v_lshlrev_b64 v[144:145], 9, v[4:5]
	v_ashrrev_i32_e32 v4, 5, v7
	v_ashrrev_i32_e32 v5, 31, v4
	v_lshlrev_b64 v[146:147], 9, v[4:5]
	v_ashrrev_i32_e32 v4, 5, v8
	v_ashrrev_i32_e32 v5, 31, v4
	v_lshlrev_b64 v[148:149], 9, v[4:5]
	v_ashrrev_i32_e32 v4, 5, v9
	v_ashrrev_i32_e32 v5, 31, v4
	v_lshlrev_b64 v[150:151], 9, v[4:5]
	v_ashrrev_i32_e32 v4, 5, v10
	v_ashrrev_i32_e32 v5, 31, v4
	v_lshlrev_b64 v[152:153], 9, v[4:5]
	v_ashrrev_i32_e32 v4, 5, v11
	v_ashrrev_i32_e32 v5, 31, v4
	v_lshlrev_b64 v[154:155], 9, v[4:5]
	v_ashrrev_i32_e32 v4, 5, v12
	v_ashrrev_i32_e32 v5, 31, v4
	v_lshlrev_b64 v[156:157], 9, v[4:5]
	v_lshlrev_b32_e32 v4, 5, v0
	v_ashrrev_i32_e32 v1, 5, v0
	v_and_or_b32 v120, v0, 31, s73
	v_lshlrev_b32_e32 v2, 3, v0
	v_and_b32_e32 v5, 0x1e0, v4
	s_mov_b32 s24, 0xffffe00
	v_and_b32_e32 v0, 28, v0
	v_lshrrev_b32_e32 v23, 10, v6
	v_and_or_b32 v16, v6, s24, v5
	v_and_b32_e32 v4, 0x60, v4
	v_add_lshl_u32 v23, v23, v0, 7
	v_bfe_u32 v6, v6, 5, 5
	s_add_u32 s34, s26, 0x2a00000
	v_and_or_b32 v17, v7, s24, v5
	v_and_or_b32 v19, v9, s24, v5
	v_and_or_b32 v21, v11, s24, v5
	v_lshrrev_b32_e32 v22, 10, v3
	v_or3_b32 v6, v23, v6, v4
	v_lshrrev_b32_e32 v7, 10, v7
	v_lshrrev_b32_e32 v23, 10, v8
	v_lshrrev_b32_e32 v9, 10, v9
	v_lshrrev_b32_e32 v11, 10, v11
	s_addc_u32 s35, s27, 0
	v_and_b32_e32 v14, 0x1f0, v3
	v_and_or_b32 v15, v3, s24, v5
	v_and_or_b32 v18, v8, s24, v5
	v_add_lshl_u32 v22, v22, v0, 7
	v_bfe_u32 v3, v3, 5, 5
	v_add_lshl_u32 v7, v7, v0, 7
	v_add_lshl_u32 v23, v23, v0, 7
	v_bfe_u32 v8, v8, 5, 5
	v_add_lshl_u32 v9, v9, v0, 7
	v_add_lshl_u32 v11, v11, v0, 7
	s_add_u32 s12, s26, 0x7c00000
	v_or3_b32 v22, v22, v3, v4
	v_or3_b32 v7, v7, v3, v4
	v_or3_b32 v8, v23, v8, v4
	v_or3_b32 v9, v9, v3, v4
	v_lshrrev_b32_e32 v23, 10, v10
	v_or3_b32 v3, v11, v3, v4
	v_lshrrev_b32_e32 v11, 10, v12
	s_addc_u32 s13, s27, 0
	v_and_or_b32 v20, v10, s24, v5
	v_add_lshl_u32 v23, v23, v0, 7
	v_bfe_u32 v10, v10, 5, 5
	v_add_lshl_u32 v0, v11, v0, 7
	v_bfe_u32 v11, v12, 5, 5
	s_add_u32 s14, s26, 0x9c00000
	v_and_or_b32 v5, v12, s24, v5
	v_or3_b32 v10, v23, v10, v4
	v_or3_b32 v0, v0, v11, v4
	s_addc_u32 s15, s27, 0
	v_lshlrev_b32_e32 v122, 3, v1
	v_and_b32_e32 v2, 0x78, v2
	v_add_u32_e32 v14, 0, v14
	v_lshlrev_b32_e32 v15, 4, v15
	v_lshlrev_b32_e32 v16, 4, v16
	v_lshlrev_b32_e32 v17, 4, v17
	v_lshlrev_b32_e32 v18, 4, v18
	v_lshlrev_b32_e32 v19, 4, v19
	v_lshlrev_b32_e32 v20, 4, v20
	v_lshlrev_b32_e32 v21, 4, v21
	v_lshlrev_b32_e32 v5, 4, v5
	v_lshlrev_b32_e32 v22, 4, v22
	v_lshlrev_b32_e32 v6, 4, v6
	v_lshlrev_b32_e32 v7, 4, v7
	v_lshlrev_b32_e32 v8, 4, v8
	v_lshlrev_b32_e32 v9, 4, v9
	v_lshlrev_b32_e32 v10, 4, v10
	v_lshlrev_b32_e32 v3, 4, v3
	v_lshlrev_b32_e32 v0, 4, v0
	v_lshlrev_b32_e32 v158, 2, v1
	s_add_i32 s24, 0, 0x10000
	v_ashrrev_i32_e32 v123, 31, v122
	s_mov_b32 s27, 0
	v_add_u32_e32 v164, 0, v13
	v_ashrrev_i32_e32 v159, 31, v158
	v_lshlrev_b64 v[160:161], 10, v[120:121]
	v_lshlrev_b32_e32 v120, 1, v2
	v_add_u32_e32 v165, v14, v15
	v_add_u32_e32 v166, v14, v16
	v_add_u32_e32 v167, v14, v17
	v_add_u32_e32 v168, v14, v18
	v_add_u32_e32 v169, v14, v19
	v_add_u32_e32 v170, v14, v20
	v_add_u32_e32 v171, v14, v21
	v_add_u32_e32 v172, v14, v5
	v_add_u32_e32 v173, s24, v22
	v_add_u32_e32 v174, s24, v6
	v_add_u32_e32 v175, s24, v7
	v_add_u32_e32 v176, s24, v8
	v_add_u32_e32 v177, s24, v9
	v_add_u32_e32 v178, s24, v10
	v_add_u32_e32 v179, s24, v3
	v_add_u32_e32 v180, s24, v0
	s_mov_b32 s36, 0
	s_branch .LBB0_657

; __global__ void __launch_bounds__(NTHR, 2) hybrid_fwd(Args args) {
	.amdhsa_kernel _Z10hybrid_fwd4Args
		.amdhsa_group_segment_fixed_size 0
		.amdhsa_private_segment_fixed_size 0
		.amdhsa_kernarg_size 432
		.amdhsa_user_sgpr_count 2
		.amdhsa_user_sgpr_dispatch_ptr 0
		.amdhsa_user_sgpr_queue_ptr 0
		.amdhsa_user_sgpr_kernarg_segment_ptr 1
		.amdhsa_user_sgpr_dispatch_id 0
		.amdhsa_user_sgpr_kernarg_preload_length 0
		.amdhsa_user_sgpr_kernarg_preload_offset 0
		.amdhsa_user_sgpr_private_segment_size 0
		.amdhsa_uses_dynamic_stack 0
		.amdhsa_enable_private_segment 0
		.amdhsa_system_sgpr_workgroup_id_x 1
		.amdhsa_system_sgpr_workgroup_id_y 0
		.amdhsa_system_sgpr_workgroup_id_z 0
		.amdhsa_system_sgpr_workgroup_info 0
		.amdhsa_system_vgpr_workitem_id 2
		.amdhsa_next_free_vgpr 249
		.amdhsa_next_free_sgpr 102
		.amdhsa_accum_offset 252
		.amdhsa_reserve_vcc 1
		.amdhsa_float_round_mode_32 0
		.amdhsa_float_round_mode_16_64 0
		.amdhsa_float_denorm_mode_32 3
		.amdhsa_float_denorm_mode_16_64 3
		.amdhsa_dx10_clamp 1
		.amdhsa_ieee_mode 1
		.amdhsa_fp16_overflow 0
		.amdhsa_tg_split 0
		.amdhsa_exception_fp_ieee_invalid_op 0
		.amdhsa_exception_fp_denorm_src 0
		.amdhsa_exception_fp_ieee_div_zero 0
		.amdhsa_exception_fp_ieee_overflow 0
		.amdhsa_exception_fp_ieee_underflow 0
		.amdhsa_exception_fp_ieee_inexact 0
		.amdhsa_exception_int_div_zero 0
	.end_amdhsa_kernel

; __global__ void __launch_bounds__(NTHR, 2) hybrid_fwd(Args args) {
amdhsa.kernels:
  - .agpr_count:     0
    .args:
      - .offset:         0
        .size:           176
        .value_kind:     by_value
      - .offset:         176
        .size:           4
        .value_kind:     hidden_block_count_x
      - .offset:         180
        .size:           4
        .value_kind:     hidden_block_count_y
      - .offset:         184
        .size:           4
        .value_kind:     hidden_block_count_z
      - .offset:         188
        .size:           2
        .value_kind:     hidden_group_size_x
      - .offset:         190
        .size:           2
        .value_kind:     hidden_group_size_y
      - .offset:         192
        .size:           2
        .value_kind:     hidden_group_size_z
      - .offset:         194
        .size:           2
        .value_kind:     hidden_remainder_x
      - .offset:         196
        .size:           2
        .value_kind:     hidden_remainder_y
      - .offset:         198
        .size:           2
        .value_kind:     hidden_remainder_z
      - .offset:         216
        .size:           8
        .value_kind:     hidden_global_offset_x
      - .offset:         224
        .size:           8
        .value_kind:     hidden_global_offset_y
      - .offset:         232
        .size:           8
        .value_kind:     hidden_global_offset_z
      - .offset:         240
        .size:           2
        .value_kind:     hidden_grid_dims
      - .offset:         264
        .size:           8
        .value_kind:     hidden_multigrid_sync_arg
      - .offset:         296
        .size:           4
        .value_kind:     hidden_dynamic_lds_size
    .group_segment_fixed_size: 0
    .kernarg_segment_align: 8
    .kernarg_segment_size: 432
    .language:       OpenCL C
    .language_version:
      - 2
      - 0
    .max_flat_workgroup_size: 512
    .name:           _Z10hybrid_fwd4Args
    .private_segment_fixed_size: 0
    .sgpr_count:     108
    .sgpr_spill_count: 6
    .symbol:         _Z10hybrid_fwd4Args.kd
    .uniform_work_group_size: 1
    .uses_dynamic_stack: false
    .vgpr_count:     249
    .vgpr_spill_count: 0
    .wavefront_size: 64
